# softmax denominator accumulated in two interleaved partial sums
# speedup vs baseline: 1.0005x; 1.0005x over previous
.Latt3_nr_5:
	v_sub_f32_e32 v82, v82, v223
	v_sub_f32_e32 v83, v83, v223
	v_sub_f32_e32 v84, v84, v223
	v_sub_f32_e32 v85, v85, v223
	v_exp_f32_e32 v82, v82
	v_exp_f32_e32 v83, v83
	v_exp_f32_e32 v84, v84
	v_exp_f32_e32 v85, v85
	v_sub_f32_e32 v86, v86, v223
	v_sub_f32_e32 v87, v87, v223
	v_sub_f32_e32 v88, v88, v223
	v_sub_f32_e32 v89, v89, v223
	v_exp_f32_e32 v86, v86
	v_exp_f32_e32 v87, v87
	v_exp_f32_e32 v88, v88
	v_exp_f32_e32 v89, v89
	v_cvt_pk_bf16_f32 v226, v82, v83
	v_cvt_pk_bf16_f32 v227, v84, v85
	v_cvt_pk_bf16_f32 v228, v86, v87
	v_cvt_pk_bf16_f32 v229, v88, v89
	s_nop 1
	v_mfma_f32_32x32x16_bf16 v[50:65], v[236:239], v[226:229], v[50:65]
	ds_read_b128 v[236:239], v205 offset:30240
	v_sub_f32_e32 v90, v90, v223
	v_sub_f32_e32 v91, v91, v223
	v_sub_f32_e32 v92, v92, v223
	v_sub_f32_e32 v93, v93, v223
	v_exp_f32_e32 v90, v90
	v_exp_f32_e32 v91, v91
	v_mfma_f32_32x32x16_bf16 v[34:49], v[240:243], v[226:229], v[34:49]
	ds_read_b128 v[240:243], v205 offset:34848
	v_exp_f32_e32 v92, v92
	v_exp_f32_e32 v93, v93
	v_sub_f32_e32 v94, v94, v223
	v_sub_f32_e32 v95, v95, v223
	v_sub_f32_e32 v96, v96, v223
	v_sub_f32_e32 v97, v97, v223
	v_mfma_f32_32x32x16_bf16 v[18:33], v[244:247], v[226:229], v[18:33]
	ds_read_b128 v[244:247], v205 offset:39456
	v_exp_f32_e32 v94, v94
	v_exp_f32_e32 v95, v95
	v_exp_f32_e32 v96, v96
	v_exp_f32_e32 v97, v97
	v_add_f32_e32 v186, 0, v82
	v_add_f32_e32 v187, 0, v86
	v_mfma_f32_32x32x16_bf16 v[2:17], v[248:251], v[226:229], v[2:17]
	ds_read_b128 v[248:251], v205 offset:25664
	v_add_f32_e32 v186, v83, v186
	v_add_f32_e32 v187, v87, v187
	v_add_f32_e32 v186, v84, v186
	v_add_f32_e32 v187, v88, v187
	v_add_f32_e32 v186, v85, v186
	v_add_f32_e32 v187, v89, v187
	v_cvt_pk_bf16_f32 v226, v90, v91
	v_cvt_pk_bf16_f32 v227, v92, v93
	v_cvt_pk_bf16_f32 v228, v94, v95
	v_cvt_pk_bf16_f32 v229, v96, v97
	s_nop 1
	v_mfma_f32_32x32x16_bf16 v[50:65], v[210:213], v[226:229], v[50:65]
	ds_read_b128 v[210:213], v205 offset:30272
	v_sub_f32_e32 v66, v66, v223
	v_sub_f32_e32 v67, v67, v223
	v_sub_f32_e32 v68, v68, v223
	v_sub_f32_e32 v69, v69, v223
	v_exp_f32_e32 v66, v66
	v_exp_f32_e32 v67, v67
	s_waitcnt lgkmcnt(4)
	v_mfma_f32_32x32x16_bf16 v[34:49], v[236:239], v[226:229], v[34:49]
	ds_read_b128 v[236:239], v205 offset:34880
	v_exp_f32_e32 v68, v68
	v_exp_f32_e32 v69, v69
	v_sub_f32_e32 v70, v70, v223
	v_sub_f32_e32 v71, v71, v223
	v_sub_f32_e32 v72, v72, v223
	v_sub_f32_e32 v73, v73, v223
	s_waitcnt lgkmcnt(4)
	v_mfma_f32_32x32x16_bf16 v[18:33], v[240:243], v[226:229], v[18:33]
	ds_read_b128 v[240:243], v205 offset:39488
	v_exp_f32_e32 v70, v70
	v_exp_f32_e32 v71, v71
	v_exp_f32_e32 v72, v72
	v_exp_f32_e32 v73, v73
	v_add_f32_e32 v186, v90, v186
	v_add_f32_e32 v187, v94, v187
	s_waitcnt lgkmcnt(4)
	v_mfma_f32_32x32x16_bf16 v[2:17], v[244:247], v[226:229], v[2:17]
	ds_read_b128 v[244:247], v205 offset:25696
	v_add_f32_e32 v186, v91, v186
	v_add_f32_e32 v187, v95, v187
	v_add_f32_e32 v186, v92, v186
	v_add_f32_e32 v187, v96, v187
	v_add_f32_e32 v186, v93, v186
	v_add_f32_e32 v187, v97, v187
	v_cvt_pk_bf16_f32 v226, v66, v67
	v_cvt_pk_bf16_f32 v227, v68, v69
	v_cvt_pk_bf16_f32 v228, v70, v71
	v_cvt_pk_bf16_f32 v229, v72, v73
	s_nop 1
	s_waitcnt lgkmcnt(4)
	v_mfma_f32_32x32x16_bf16 v[50:65], v[248:251], v[226:229], v[50:65]
	ds_read_b128 v[248:251], v205 offset:30304
	v_sub_f32_e32 v74, v74, v223
	v_sub_f32_e32 v75, v75, v223
	v_sub_f32_e32 v76, v76, v223
	v_sub_f32_e32 v77, v77, v223
	v_exp_f32_e32 v74, v74
	v_exp_f32_e32 v75, v75
	s_waitcnt lgkmcnt(4)
	v_mfma_f32_32x32x16_bf16 v[34:49], v[210:213], v[226:229], v[34:49]
	ds_read_b128 v[210:213], v205 offset:34912
	v_exp_f32_e32 v76, v76
	v_exp_f32_e32 v77, v77
	v_sub_f32_e32 v78, v78, v223
	v_sub_f32_e32 v79, v79, v223
	v_sub_f32_e32 v80, v80, v223
	v_sub_f32_e32 v81, v81, v223
	s_waitcnt lgkmcnt(4)
	v_mfma_f32_32x32x16_bf16 v[18:33], v[236:239], v[226:229], v[18:33]
	ds_read_b128 v[236:239], v205 offset:39520
	v_exp_f32_e32 v78, v78
	v_exp_f32_e32 v79, v79
	v_exp_f32_e32 v80, v80
	v_exp_f32_e32 v81, v81
	v_add_f32_e32 v186, v66, v186
	v_add_f32_e32 v187, v70, v187
	s_waitcnt lgkmcnt(4)
	v_mfma_f32_32x32x16_bf16 v[2:17], v[240:243], v[226:229], v[2:17]
	v_add_f32_e32 v186, v67, v186
	v_add_f32_e32 v187, v71, v187
	v_add_f32_e32 v186, v68, v186
	v_add_f32_e32 v187, v72, v187
	v_add_f32_e32 v186, v69, v186
	v_add_f32_e32 v187, v73, v187
	v_cvt_pk_bf16_f32 v226, v74, v75
	v_cvt_pk_bf16_f32 v227, v76, v77
	v_cvt_pk_bf16_f32 v228, v78, v79
	v_cvt_pk_bf16_f32 v229, v80, v81
	s_nop 1
	s_waitcnt lgkmcnt(3)
	v_mfma_f32_32x32x16_bf16 v[50:65], v[244:247], v[226:229], v[50:65]
	v_add_f32_e32 v186, v74, v186
	v_add_f32_e32 v187, v78, v187
	s_waitcnt lgkmcnt(2)
	v_mfma_f32_32x32x16_bf16 v[34:49], v[248:251], v[226:229], v[34:49]
	v_add_f32_e32 v186, v75, v186
	v_add_f32_e32 v187, v79, v187
	s_waitcnt lgkmcnt(1)
	v_mfma_f32_32x32x16_bf16 v[18:33], v[210:213], v[226:229], v[18:33]
	v_add_f32_e32 v186, v76, v186
	v_add_f32_e32 v187, v80, v187
	s_waitcnt lgkmcnt(0)
	s_barrier
	v_mfma_f32_32x32x16_bf16 v[2:17], v[236:239], v[226:229], v[2:17]
	v_add_f32_e32 v186, v77, v186
	v_add_f32_e32 v187, v81, v187
	v_add_f32_e32 v186, v186, v187
	v_add_f32_e32 v225, v224, v186
	s_setprio 0
	s_add_i32 s13, s11, 2
	s_cmp_ge_u32 s13, s5
	s_cbranch_scc1 .Latt3_wskip_6
	v_add_u32_e32 v206, s72, v219
	v_add_u32_e32 v208, s72, v220
	v_add_u32_e32 v186, s72, v221
	v_add_u32_e32 v187, s72, v222
	s_add_i32 s13, s11, 3
	s_cmp_ge_u32 s13, s5
	s_cbranch_scc1 .Latt3_wtail_7
	s_waitcnt vmcnt(9)
	ds_write_b128 v206, v[118:121]
	s_waitcnt vmcnt(8)
	ds_write_b128 v208, v[122:125]
	s_waitcnt vmcnt(7)
	ds_write_b128 v186, v[130:133]
	s_waitcnt vmcnt(6)
	ds_write_b128 v187, v[134:137] offset:25600
	s_waitcnt vmcnt(5)
	ds_write_b128 v187, v[138:141] offset:34816
	s_branch .Latt3_wld_8

.Latt3_nr_10:
	v_sub_f32_e32 v82, v82, v223
	v_sub_f32_e32 v83, v83, v223
	v_sub_f32_e32 v84, v84, v223
	v_sub_f32_e32 v85, v85, v223
	v_exp_f32_e32 v82, v82
	v_exp_f32_e32 v83, v83
	v_exp_f32_e32 v84, v84
	v_exp_f32_e32 v85, v85
	v_sub_f32_e32 v86, v86, v223
	v_sub_f32_e32 v87, v87, v223
	v_sub_f32_e32 v88, v88, v223
	v_sub_f32_e32 v89, v89, v223
	v_exp_f32_e32 v86, v86
	v_exp_f32_e32 v87, v87
	v_exp_f32_e32 v88, v88
	v_exp_f32_e32 v89, v89
	v_cvt_pk_bf16_f32 v226, v82, v83
	v_cvt_pk_bf16_f32 v227, v84, v85
	v_cvt_pk_bf16_f32 v228, v86, v87
	v_cvt_pk_bf16_f32 v229, v88, v89
	s_nop 1
	v_mfma_f32_32x32x16_bf16 v[50:65], v[236:239], v[226:229], v[50:65]
	ds_read_b128 v[236:239], v205 offset:30240
	v_sub_f32_e32 v90, v90, v223
	v_sub_f32_e32 v91, v91, v223
	v_sub_f32_e32 v92, v92, v223
	v_sub_f32_e32 v93, v93, v223
	v_exp_f32_e32 v90, v90
	v_exp_f32_e32 v91, v91
	v_mfma_f32_32x32x16_bf16 v[34:49], v[240:243], v[226:229], v[34:49]
	ds_read_b128 v[240:243], v205 offset:34848
	v_exp_f32_e32 v92, v92
	v_exp_f32_e32 v93, v93
	v_sub_f32_e32 v94, v94, v223
	v_sub_f32_e32 v95, v95, v223
	v_sub_f32_e32 v96, v96, v223
	v_sub_f32_e32 v97, v97, v223
	v_mfma_f32_32x32x16_bf16 v[18:33], v[244:247], v[226:229], v[18:33]
	ds_read_b128 v[244:247], v205 offset:39456
	v_exp_f32_e32 v94, v94
	v_exp_f32_e32 v95, v95
	v_exp_f32_e32 v96, v96
	v_exp_f32_e32 v97, v97
	v_add_f32_e32 v186, 0, v82
	v_add_f32_e32 v187, 0, v86
	v_mfma_f32_32x32x16_bf16 v[2:17], v[248:251], v[226:229], v[2:17]
	ds_read_b128 v[248:251], v205 offset:25664
	v_add_f32_e32 v186, v83, v186
	v_add_f32_e32 v187, v87, v187
	v_add_f32_e32 v186, v84, v186
	v_add_f32_e32 v187, v88, v187
	v_add_f32_e32 v186, v85, v186
	v_add_f32_e32 v187, v89, v187
	v_cvt_pk_bf16_f32 v226, v90, v91
	v_cvt_pk_bf16_f32 v227, v92, v93
	v_cvt_pk_bf16_f32 v228, v94, v95
	v_cvt_pk_bf16_f32 v229, v96, v97
	s_nop 1
	v_mfma_f32_32x32x16_bf16 v[50:65], v[210:213], v[226:229], v[50:65]
	ds_read_b128 v[210:213], v205 offset:30272
	v_sub_f32_e32 v66, v66, v223
	v_sub_f32_e32 v67, v67, v223
	v_sub_f32_e32 v68, v68, v223
	v_sub_f32_e32 v69, v69, v223
	v_exp_f32_e32 v66, v66
	v_exp_f32_e32 v67, v67
	s_waitcnt lgkmcnt(4)
	v_mfma_f32_32x32x16_bf16 v[34:49], v[236:239], v[226:229], v[34:49]
	ds_read_b128 v[236:239], v205 offset:34880
	v_exp_f32_e32 v68, v68
	v_exp_f32_e32 v69, v69
	v_sub_f32_e32 v70, v70, v223
	v_sub_f32_e32 v71, v71, v223
	v_sub_f32_e32 v72, v72, v223
	v_sub_f32_e32 v73, v73, v223
	s_waitcnt lgkmcnt(4)
	v_mfma_f32_32x32x16_bf16 v[18:33], v[240:243], v[226:229], v[18:33]
	ds_read_b128 v[240:243], v205 offset:39488
	v_exp_f32_e32 v70, v70
	v_exp_f32_e32 v71, v71
	v_exp_f32_e32 v72, v72
	v_exp_f32_e32 v73, v73
	v_add_f32_e32 v186, v90, v186
	v_add_f32_e32 v187, v94, v187
	s_waitcnt lgkmcnt(4)
	v_mfma_f32_32x32x16_bf16 v[2:17], v[244:247], v[226:229], v[2:17]
	ds_read_b128 v[244:247], v205 offset:25696
	v_add_f32_e32 v186, v91, v186
	v_add_f32_e32 v187, v95, v187
	v_add_f32_e32 v186, v92, v186
	v_add_f32_e32 v187, v96, v187
	v_add_f32_e32 v186, v93, v186
	v_add_f32_e32 v187, v97, v187
	v_cvt_pk_bf16_f32 v226, v66, v67
	v_cvt_pk_bf16_f32 v227, v68, v69
	v_cvt_pk_bf16_f32 v228, v70, v71
	v_cvt_pk_bf16_f32 v229, v72, v73
	s_nop 1
	s_waitcnt lgkmcnt(4)
	v_mfma_f32_32x32x16_bf16 v[50:65], v[248:251], v[226:229], v[50:65]
	ds_read_b128 v[248:251], v205 offset:30304
	v_sub_f32_e32 v74, v74, v223
	v_sub_f32_e32 v75, v75, v223
	v_sub_f32_e32 v76, v76, v223
	v_sub_f32_e32 v77, v77, v223
	v_exp_f32_e32 v74, v74
	v_exp_f32_e32 v75, v75
	s_waitcnt lgkmcnt(4)
	v_mfma_f32_32x32x16_bf16 v[34:49], v[210:213], v[226:229], v[34:49]
	ds_read_b128 v[210:213], v205 offset:34912
	v_exp_f32_e32 v76, v76
	v_exp_f32_e32 v77, v77
	v_sub_f32_e32 v78, v78, v223
	v_sub_f32_e32 v79, v79, v223
	v_sub_f32_e32 v80, v80, v223
	v_sub_f32_e32 v81, v81, v223
	s_waitcnt lgkmcnt(4)
	v_mfma_f32_32x32x16_bf16 v[18:33], v[236:239], v[226:229], v[18:33]
	ds_read_b128 v[236:239], v205 offset:39520
	v_exp_f32_e32 v78, v78
	v_exp_f32_e32 v79, v79
	v_exp_f32_e32 v80, v80
	v_exp_f32_e32 v81, v81
	v_add_f32_e32 v186, v66, v186
	v_add_f32_e32 v187, v70, v187
	s_waitcnt lgkmcnt(4)
	v_mfma_f32_32x32x16_bf16 v[2:17], v[240:243], v[226:229], v[2:17]
	v_add_f32_e32 v186, v67, v186
	v_add_f32_e32 v187, v71, v187
	v_add_f32_e32 v186, v68, v186
	v_add_f32_e32 v187, v72, v187
	v_add_f32_e32 v186, v69, v186
	v_add_f32_e32 v187, v73, v187
	v_cvt_pk_bf16_f32 v226, v74, v75
	v_cvt_pk_bf16_f32 v227, v76, v77
	v_cvt_pk_bf16_f32 v228, v78, v79
	v_cvt_pk_bf16_f32 v229, v80, v81
	s_nop 1
	s_waitcnt lgkmcnt(3)
	v_mfma_f32_32x32x16_bf16 v[50:65], v[244:247], v[226:229], v[50:65]
	v_add_f32_e32 v186, v74, v186
	v_add_f32_e32 v187, v78, v187
	s_waitcnt lgkmcnt(2)
	v_mfma_f32_32x32x16_bf16 v[34:49], v[248:251], v[226:229], v[34:49]
	v_add_f32_e32 v186, v75, v186
	v_add_f32_e32 v187, v79, v187
	s_waitcnt lgkmcnt(1)
	v_mfma_f32_32x32x16_bf16 v[18:33], v[210:213], v[226:229], v[18:33]
	v_add_f32_e32 v186, v76, v186
	v_add_f32_e32 v187, v80, v187
	s_waitcnt lgkmcnt(0)
	s_barrier
	v_mfma_f32_32x32x16_bf16 v[2:17], v[236:239], v[226:229], v[2:17]
	v_add_f32_e32 v186, v77, v186
	v_add_f32_e32 v187, v81, v187
	v_add_f32_e32 v186, v186, v187
	v_add_f32_e32 v224, v225, v186
	s_setprio 0
	s_add_i32 s13, s11, 2
	s_cmp_ge_u32 s13, s5
	s_cbranch_scc1 .Latt3_wskip_11
	v_add_u32_e32 v206, s72, v219
	v_add_u32_e32 v208, s72, v220
	v_add_u32_e32 v186, s72, v221
	v_add_u32_e32 v187, s72, v222
	s_add_i32 s13, s11, 3
	s_cmp_ge_u32 s13, s5
	s_cbranch_scc1 .Latt3_wtail_12
	s_waitcnt vmcnt(9)
	ds_write_b128 v206, v[102:105]
	s_waitcnt vmcnt(8)
	ds_write_b128 v208, v[106:109]
	s_waitcnt vmcnt(7)
	ds_write_b128 v186, v[114:117]
	s_waitcnt vmcnt(6)
	ds_write_b128 v187, v[98:101] offset:25600
	s_waitcnt vmcnt(5)
	ds_write_b128 v187, v[110:113] offset:34816
	s_branch .Latt3_wld_13

.Latt3_nr_15:
	v_sub_f32_e32 v82, v82, v223
	v_sub_f32_e32 v83, v83, v223
	v_sub_f32_e32 v84, v84, v223
	v_sub_f32_e32 v85, v85, v223
	v_exp_f32_e32 v82, v82
	v_exp_f32_e32 v83, v83
	v_exp_f32_e32 v84, v84
	v_exp_f32_e32 v85, v85
	v_sub_f32_e32 v86, v86, v223
	v_sub_f32_e32 v87, v87, v223
	v_sub_f32_e32 v88, v88, v223
	v_sub_f32_e32 v89, v89, v223
	v_exp_f32_e32 v86, v86
	v_exp_f32_e32 v87, v87
	v_exp_f32_e32 v88, v88
	v_exp_f32_e32 v89, v89
	v_cvt_pk_bf16_f32 v226, v82, v83
	v_cvt_pk_bf16_f32 v227, v84, v85
	v_cvt_pk_bf16_f32 v228, v86, v87
	v_cvt_pk_bf16_f32 v229, v88, v89
	s_nop 1
	v_mfma_f32_32x32x16_bf16 v[50:65], v[236:239], v[226:229], v[50:65]
	ds_read_b128 v[236:239], v205 offset:30240
	v_sub_f32_e32 v90, v90, v223
	v_sub_f32_e32 v91, v91, v223
	v_sub_f32_e32 v92, v92, v223
	v_sub_f32_e32 v93, v93, v223
	v_exp_f32_e32 v90, v90
	v_exp_f32_e32 v91, v91
	v_mfma_f32_32x32x16_bf16 v[34:49], v[240:243], v[226:229], v[34:49]
	ds_read_b128 v[240:243], v205 offset:34848
	v_exp_f32_e32 v92, v92
	v_exp_f32_e32 v93, v93
	v_sub_f32_e32 v94, v94, v223
	v_sub_f32_e32 v95, v95, v223
	v_sub_f32_e32 v96, v96, v223
	v_sub_f32_e32 v97, v97, v223
	v_mfma_f32_32x32x16_bf16 v[18:33], v[244:247], v[226:229], v[18:33]
	ds_read_b128 v[244:247], v205 offset:39456
	v_exp_f32_e32 v94, v94
	v_exp_f32_e32 v95, v95
	v_exp_f32_e32 v96, v96
	v_exp_f32_e32 v97, v97
	v_add_f32_e32 v186, 0, v82
	v_add_f32_e32 v187, 0, v86
	v_mfma_f32_32x32x16_bf16 v[2:17], v[248:251], v[226:229], v[2:17]
	ds_read_b128 v[248:251], v205 offset:25664
	v_add_f32_e32 v186, v83, v186
	v_add_f32_e32 v187, v87, v187
	v_add_f32_e32 v186, v84, v186
	v_add_f32_e32 v187, v88, v187
	v_add_f32_e32 v186, v85, v186
	v_add_f32_e32 v187, v89, v187
	v_cvt_pk_bf16_f32 v226, v90, v91
	v_cvt_pk_bf16_f32 v227, v92, v93
	v_cvt_pk_bf16_f32 v228, v94, v95
	v_cvt_pk_bf16_f32 v229, v96, v97
	s_nop 1
	v_mfma_f32_32x32x16_bf16 v[50:65], v[210:213], v[226:229], v[50:65]
	ds_read_b128 v[210:213], v205 offset:30272
	v_sub_f32_e32 v66, v66, v223
	v_sub_f32_e32 v67, v67, v223
	v_sub_f32_e32 v68, v68, v223
	v_sub_f32_e32 v69, v69, v223
	v_exp_f32_e32 v66, v66
	v_exp_f32_e32 v67, v67
	s_waitcnt lgkmcnt(4)
	v_mfma_f32_32x32x16_bf16 v[34:49], v[236:239], v[226:229], v[34:49]
	ds_read_b128 v[236:239], v205 offset:34880
	v_exp_f32_e32 v68, v68
	v_exp_f32_e32 v69, v69
	v_sub_f32_e32 v70, v70, v223
	v_sub_f32_e32 v71, v71, v223
	v_sub_f32_e32 v72, v72, v223
	v_sub_f32_e32 v73, v73, v223
	s_waitcnt lgkmcnt(4)
	v_mfma_f32_32x32x16_bf16 v[18:33], v[240:243], v[226:229], v[18:33]
	ds_read_b128 v[240:243], v205 offset:39488
	v_exp_f32_e32 v70, v70
	v_exp_f32_e32 v71, v71
	v_exp_f32_e32 v72, v72
	v_exp_f32_e32 v73, v73
	v_add_f32_e32 v186, v90, v186
	v_add_f32_e32 v187, v94, v187
	s_waitcnt lgkmcnt(4)
	v_mfma_f32_32x32x16_bf16 v[2:17], v[244:247], v[226:229], v[2:17]
	ds_read_b128 v[244:247], v205 offset:25696
	v_add_f32_e32 v186, v91, v186
	v_add_f32_e32 v187, v95, v187
	v_add_f32_e32 v186, v92, v186
	v_add_f32_e32 v187, v96, v187
	v_add_f32_e32 v186, v93, v186
	v_add_f32_e32 v187, v97, v187
	v_cvt_pk_bf16_f32 v226, v66, v67
	v_cvt_pk_bf16_f32 v227, v68, v69
	v_cvt_pk_bf16_f32 v228, v70, v71
	v_cvt_pk_bf16_f32 v229, v72, v73
	s_nop 1
	s_waitcnt lgkmcnt(4)
	v_mfma_f32_32x32x16_bf16 v[50:65], v[248:251], v[226:229], v[50:65]
	ds_read_b128 v[248:251], v205 offset:30304
	v_sub_f32_e32 v74, v74, v223
	v_sub_f32_e32 v75, v75, v223
	v_sub_f32_e32 v76, v76, v223
	v_sub_f32_e32 v77, v77, v223
	v_exp_f32_e32 v74, v74
	v_exp_f32_e32 v75, v75
	s_waitcnt lgkmcnt(4)
	v_mfma_f32_32x32x16_bf16 v[34:49], v[210:213], v[226:229], v[34:49]
	ds_read_b128 v[210:213], v205 offset:34912
	v_exp_f32_e32 v76, v76
	v_exp_f32_e32 v77, v77
	v_sub_f32_e32 v78, v78, v223
	v_sub_f32_e32 v79, v79, v223
	v_sub_f32_e32 v80, v80, v223
	v_sub_f32_e32 v81, v81, v223
	s_waitcnt lgkmcnt(4)
	v_mfma_f32_32x32x16_bf16 v[18:33], v[236:239], v[226:229], v[18:33]
	ds_read_b128 v[236:239], v205 offset:39520
	v_exp_f32_e32 v78, v78
	v_exp_f32_e32 v79, v79
	v_exp_f32_e32 v80, v80
	v_exp_f32_e32 v81, v81
	v_add_f32_e32 v186, v66, v186
	v_add_f32_e32 v187, v70, v187
	s_waitcnt lgkmcnt(4)
	v_mfma_f32_32x32x16_bf16 v[2:17], v[240:243], v[226:229], v[2:17]
	v_add_f32_e32 v186, v67, v186
	v_add_f32_e32 v187, v71, v187
	v_add_f32_e32 v186, v68, v186
	v_add_f32_e32 v187, v72, v187
	v_add_f32_e32 v186, v69, v186
	v_add_f32_e32 v187, v73, v187
	v_cvt_pk_bf16_f32 v226, v74, v75
	v_cvt_pk_bf16_f32 v227, v76, v77
	v_cvt_pk_bf16_f32 v228, v78, v79
	v_cvt_pk_bf16_f32 v229, v80, v81
	s_nop 1
	s_waitcnt lgkmcnt(3)
	v_mfma_f32_32x32x16_bf16 v[50:65], v[244:247], v[226:229], v[50:65]
	v_add_f32_e32 v186, v74, v186
	v_add_f32_e32 v187, v78, v187
	s_waitcnt lgkmcnt(2)
	v_mfma_f32_32x32x16_bf16 v[34:49], v[248:251], v[226:229], v[34:49]
	v_add_f32_e32 v186, v75, v186
	v_add_f32_e32 v187, v79, v187
	s_waitcnt lgkmcnt(1)
	v_mfma_f32_32x32x16_bf16 v[18:33], v[210:213], v[226:229], v[18:33]
	v_add_f32_e32 v186, v76, v186
	v_add_f32_e32 v187, v80, v187
	s_waitcnt lgkmcnt(0)
	v_mfma_f32_32x32x16_bf16 v[2:17], v[236:239], v[226:229], v[2:17]
	v_add_f32_e32 v186, v77, v186
	v_add_f32_e32 v187, v81, v187
	v_add_f32_e32 v186, v186, v187
	v_add_f32_e32 v225, v224, v186
	s_setprio 0
	s_add_i32 s13, s11, 2
	s_cmp_ge_u32 s13, s5
	s_cbranch_scc1 .Latt3_wskip_16
	v_add_u32_e32 v206, s72, v219
	v_add_u32_e32 v208, s72, v220
	v_add_u32_e32 v186, s72, v221
	v_add_u32_e32 v187, s72, v222
	s_add_i32 s13, s11, 3
	s_cmp_ge_u32 s13, s5
	s_cbranch_scc1 .Latt3_wtail_17
	s_waitcnt vmcnt(9)
	ds_write_b128 v206, v[118:121]
	s_waitcnt vmcnt(8)
	ds_write_b128 v208, v[122:125]
	s_waitcnt vmcnt(7)
	ds_write_b128 v186, v[130:133]
	s_waitcnt vmcnt(6)
	ds_write_b128 v187, v[134:137] offset:25600
	s_waitcnt vmcnt(5)
	ds_write_b128 v187, v[138:141] offset:34816
	s_branch .Latt3_wld_18

.Latt3_nr_20:
	v_sub_f32_e32 v82, v82, v223
	v_sub_f32_e32 v83, v83, v223
	v_sub_f32_e32 v84, v84, v223
	v_sub_f32_e32 v85, v85, v223
	v_exp_f32_e32 v82, v82
	v_exp_f32_e32 v83, v83
	v_exp_f32_e32 v84, v84
	v_exp_f32_e32 v85, v85
	v_sub_f32_e32 v86, v86, v223
	v_sub_f32_e32 v87, v87, v223
	v_sub_f32_e32 v88, v88, v223
	v_sub_f32_e32 v89, v89, v223
	v_exp_f32_e32 v86, v86
	v_exp_f32_e32 v87, v87
	v_exp_f32_e32 v88, v88
	v_exp_f32_e32 v89, v89
	v_cvt_pk_bf16_f32 v226, v82, v83
	v_cvt_pk_bf16_f32 v227, v84, v85
	v_cvt_pk_bf16_f32 v228, v86, v87
	v_cvt_pk_bf16_f32 v229, v88, v89
	s_nop 1
	v_mfma_f32_32x32x16_bf16 v[50:65], v[236:239], v[226:229], v[50:65]
	ds_read_b128 v[236:239], v205 offset:30240
	v_sub_f32_e32 v90, v90, v223
	v_sub_f32_e32 v91, v91, v223
	v_sub_f32_e32 v92, v92, v223
	v_sub_f32_e32 v93, v93, v223
	v_exp_f32_e32 v90, v90
	v_exp_f32_e32 v91, v91
	v_mfma_f32_32x32x16_bf16 v[34:49], v[240:243], v[226:229], v[34:49]
	ds_read_b128 v[240:243], v205 offset:34848
	v_exp_f32_e32 v92, v92
	v_exp_f32_e32 v93, v93
	v_sub_f32_e32 v94, v94, v223
	v_sub_f32_e32 v95, v95, v223
	v_sub_f32_e32 v96, v96, v223
	v_sub_f32_e32 v97, v97, v223
	v_mfma_f32_32x32x16_bf16 v[18:33], v[244:247], v[226:229], v[18:33]
	ds_read_b128 v[244:247], v205 offset:39456
	v_exp_f32_e32 v94, v94
	v_exp_f32_e32 v95, v95
	v_exp_f32_e32 v96, v96
	v_exp_f32_e32 v97, v97
	v_add_f32_e32 v186, 0, v82
	v_add_f32_e32 v187, 0, v86
	v_mfma_f32_32x32x16_bf16 v[2:17], v[248:251], v[226:229], v[2:17]
	ds_read_b128 v[248:251], v205 offset:25664
	v_add_f32_e32 v186, v83, v186
	v_add_f32_e32 v187, v87, v187
	v_add_f32_e32 v186, v84, v186
	v_add_f32_e32 v187, v88, v187
	v_add_f32_e32 v186, v85, v186
	v_add_f32_e32 v187, v89, v187
	v_cvt_pk_bf16_f32 v226, v90, v91
	v_cvt_pk_bf16_f32 v227, v92, v93
	v_cvt_pk_bf16_f32 v228, v94, v95
	v_cvt_pk_bf16_f32 v229, v96, v97
	s_nop 1
	v_mfma_f32_32x32x16_bf16 v[50:65], v[210:213], v[226:229], v[50:65]
	ds_read_b128 v[210:213], v205 offset:30272
	v_sub_f32_e32 v66, v66, v223
	v_sub_f32_e32 v67, v67, v223
	v_sub_f32_e32 v68, v68, v223
	v_sub_f32_e32 v69, v69, v223
	v_exp_f32_e32 v66, v66
	v_exp_f32_e32 v67, v67
	s_waitcnt lgkmcnt(4)
	v_mfma_f32_32x32x16_bf16 v[34:49], v[236:239], v[226:229], v[34:49]
	ds_read_b128 v[236:239], v205 offset:34880
	v_exp_f32_e32 v68, v68
	v_exp_f32_e32 v69, v69
	v_sub_f32_e32 v70, v70, v223
	v_sub_f32_e32 v71, v71, v223
	v_sub_f32_e32 v72, v72, v223
	v_sub_f32_e32 v73, v73, v223
	s_waitcnt lgkmcnt(4)
	v_mfma_f32_32x32x16_bf16 v[18:33], v[240:243], v[226:229], v[18:33]
	ds_read_b128 v[240:243], v205 offset:39488
	v_exp_f32_e32 v70, v70
	v_exp_f32_e32 v71, v71
	v_exp_f32_e32 v72, v72
	v_exp_f32_e32 v73, v73
	v_add_f32_e32 v186, v90, v186
	v_add_f32_e32 v187, v94, v187
	s_waitcnt lgkmcnt(4)
	v_mfma_f32_32x32x16_bf16 v[2:17], v[244:247], v[226:229], v[2:17]
	ds_read_b128 v[244:247], v205 offset:25696
	v_add_f32_e32 v186, v91, v186
	v_add_f32_e32 v187, v95, v187
	v_add_f32_e32 v186, v92, v186
	v_add_f32_e32 v187, v96, v187
	v_add_f32_e32 v186, v93, v186
	v_add_f32_e32 v187, v97, v187
	v_cvt_pk_bf16_f32 v226, v66, v67
	v_cvt_pk_bf16_f32 v227, v68, v69
	v_cvt_pk_bf16_f32 v228, v70, v71
	v_cvt_pk_bf16_f32 v229, v72, v73
	s_nop 1
	s_waitcnt lgkmcnt(4)
	v_mfma_f32_32x32x16_bf16 v[50:65], v[248:251], v[226:229], v[50:65]
	ds_read_b128 v[248:251], v205 offset:30304
	v_sub_f32_e32 v74, v74, v223
	v_sub_f32_e32 v75, v75, v223
	v_sub_f32_e32 v76, v76, v223
	v_sub_f32_e32 v77, v77, v223
	v_exp_f32_e32 v74, v74
	v_exp_f32_e32 v75, v75
	s_waitcnt lgkmcnt(4)
	v_mfma_f32_32x32x16_bf16 v[34:49], v[210:213], v[226:229], v[34:49]
	ds_read_b128 v[210:213], v205 offset:34912
	v_exp_f32_e32 v76, v76
	v_exp_f32_e32 v77, v77
	v_sub_f32_e32 v78, v78, v223
	v_sub_f32_e32 v79, v79, v223
	v_sub_f32_e32 v80, v80, v223
	v_sub_f32_e32 v81, v81, v223
	s_waitcnt lgkmcnt(4)
	v_mfma_f32_32x32x16_bf16 v[18:33], v[236:239], v[226:229], v[18:33]
	ds_read_b128 v[236:239], v205 offset:39520
	v_exp_f32_e32 v78, v78
	v_exp_f32_e32 v79, v79
	v_exp_f32_e32 v80, v80
	v_exp_f32_e32 v81, v81
	v_add_f32_e32 v186, v66, v186
	v_add_f32_e32 v187, v70, v187
	s_waitcnt lgkmcnt(4)
	v_mfma_f32_32x32x16_bf16 v[2:17], v[240:243], v[226:229], v[2:17]
	v_add_f32_e32 v186, v67, v186
	v_add_f32_e32 v187, v71, v187
	v_add_f32_e32 v186, v68, v186
	v_add_f32_e32 v187, v72, v187
	v_add_f32_e32 v186, v69, v186
	v_add_f32_e32 v187, v73, v187
	v_cvt_pk_bf16_f32 v226, v74, v75
	v_cvt_pk_bf16_f32 v227, v76, v77
	v_cvt_pk_bf16_f32 v228, v78, v79
	v_cvt_pk_bf16_f32 v229, v80, v81
	s_nop 1
	s_waitcnt lgkmcnt(3)
	v_mfma_f32_32x32x16_bf16 v[50:65], v[244:247], v[226:229], v[50:65]
	v_add_f32_e32 v186, v74, v186
	v_add_f32_e32 v187, v78, v187
	s_waitcnt lgkmcnt(2)
	v_mfma_f32_32x32x16_bf16 v[34:49], v[248:251], v[226:229], v[34:49]
	v_add_f32_e32 v186, v75, v186
	v_add_f32_e32 v187, v79, v187
	s_waitcnt lgkmcnt(1)
	v_mfma_f32_32x32x16_bf16 v[18:33], v[210:213], v[226:229], v[18:33]
	v_add_f32_e32 v186, v76, v186
	v_add_f32_e32 v187, v80, v187
	s_waitcnt lgkmcnt(0)
	v_mfma_f32_32x32x16_bf16 v[2:17], v[236:239], v[226:229], v[2:17]
	v_add_f32_e32 v186, v77, v186
	v_add_f32_e32 v187, v81, v187
	v_add_f32_e32 v186, v186, v187
	v_add_f32_e32 v224, v225, v186
	s_setprio 0
	s_add_i32 s13, s11, 2
	s_cmp_ge_u32 s13, s5
	s_cbranch_scc1 .Latt3_wskip_21
	v_add_u32_e32 v206, s72, v219
	v_add_u32_e32 v208, s72, v220
	v_add_u32_e32 v186, s72, v221
	v_add_u32_e32 v187, s72, v222
	s_add_i32 s13, s11, 3
	s_cmp_ge_u32 s13, s5
	s_cbranch_scc1 .Latt3_wtail_22
	s_waitcnt vmcnt(9)
	ds_write_b128 v206, v[102:105]
	s_waitcnt vmcnt(8)
	ds_write_b128 v208, v[106:109]
	s_waitcnt vmcnt(7)
	ds_write_b128 v186, v[114:117]
	s_waitcnt vmcnt(6)
	ds_write_b128 v187, v[98:101] offset:25600
	s_waitcnt vmcnt(5)
	ds_write_b128 v187, v[110:113] offset:34816
	s_branch .Latt3_wld_23
